# P3 CU/GB epilogue paths rewritten by hand (no runtime isgb shuffles) + P3 tile rebalance + peeled K-loop + saddr DMA
# speedup vs baseline: 1.0028x; 1.0028x over previous
.LBB0_463:
	s_add_i32 s46, s40, s6
	s_sub_i32 s98, s46, 11
	s_cmp_lt_u32 s98, 3
	s_cselect_b32 s99, 7, 0
	s_sub_i32 s98, s46, 18
	s_cmp_lt_u32 s98, 3
	s_cselect_b32 s98, 0xfffffff9, 0
	s_add_i32 s99, s99, s98
	s_cmp_eq_u32 s46, 6
	s_cselect_b32 s98, 11, 0
	s_add_i32 s99, s99, s98
	s_cmp_eq_u32 s46, 17
	s_cselect_b32 s98, 0xfffffff5, 0
	s_add_i32 s99, s99, s98
	s_add_i32 s46, s46, s99
	s_sub_i32 s4, s46, 22
	s_cmp_gt_u32 s4, 0xffffffef
	s_mov_b64 s[4:5], -1
	s_cbranch_scc0 .LBB0_529
	s_lshl_b32 s4, s40, 10
	v_add_u32_e32 v196, s4, v176
	ds_read_b32 v134, v196
	s_cmp_gt_u32 s46, 13
	v_readlane_b32 s9, v253, 53
	s_cselect_b32 s8, s76, s80
	s_cselect_b32 s9, s9, s81
	s_lshl_b32 s35, s46, 7
	s_addk_i32 s35, 0x100
	s_lshr_b32 s35, s35, 5
	s_and_b32 s35, s35, 28
	s_or_b32 s35, s35, s90
	s_and_b32 s9, s9, 0xffff
	v_lshl_or_b32 v195, s35, 6, v163
	s_cmp_gt_u32 s46, 13
	s_cbranch_scc1 .Lp3_gb_path
	s_waitcnt lgkmcnt(0)
	v_mul_f32_e32 v130, v134, v134
	ds_read_b32 v134, v196 offset:64
	v_pk_mul_f32 v[122:123], v[122:123], v[114:115]
	v_pk_mul_f32 v[124:125], v[124:125], v[116:117]
	v_pk_mul_f32 v[126:127], v[118:119], v[126:127]
	v_pk_mul_f32 v[128:129], v[120:121], v[128:129]
	v_pk_mul_f32 v[122:123], v[122:123], v[130:131] op_sel_hi:[1,0]
	v_pk_mul_f32 v[124:125], v[124:125], v[130:131] op_sel_hi:[1,0]
	v_pk_mul_f32 v[126:127], v[126:127], v[130:131] op_sel_hi:[1,0]
	v_pk_mul_f32 v[128:129], v[128:129], v[130:131] op_sel_hi:[1,0]
	v_or_b32_e32 v140, v156, v195
	v_lshlrev_b32_e32 v140, 1, v140
	s_nop 0
	v_cvt_pk_bf16_f32 v136, v122, v123
	v_cvt_pk_bf16_f32 v137, v124, v125
	v_cvt_pk_bf16_f32 v138, v126, v127
	v_cvt_pk_bf16_f32 v139, v128, v129
	buffer_store_dwordx4 v[136:139], v140, s[8:11], 0 offen sc1
	s_waitcnt lgkmcnt(0)
	v_mul_f32_e32 v130, v134, v134
	ds_read_b32 v134, v196 offset:128
	v_pk_mul_f32 v[106:107], v[106:107], v[98:99]
	v_pk_mul_f32 v[108:109], v[108:109], v[100:101]
	v_pk_mul_f32 v[110:111], v[102:103], v[110:111]
	v_pk_mul_f32 v[112:113], v[104:105], v[112:113]
	v_pk_mul_f32 v[106:107], v[106:107], v[130:131] op_sel_hi:[1,0]
	v_pk_mul_f32 v[108:109], v[108:109], v[130:131] op_sel_hi:[1,0]
	v_pk_mul_f32 v[110:111], v[110:111], v[130:131] op_sel_hi:[1,0]
	v_pk_mul_f32 v[112:113], v[112:113], v[130:131] op_sel_hi:[1,0]
	v_or_b32_e32 v140, v177, v195
	v_lshlrev_b32_e32 v140, 1, v140
	s_nop 0
	v_cvt_pk_bf16_f32 v136, v106, v107
	v_cvt_pk_bf16_f32 v137, v108, v109
	v_cvt_pk_bf16_f32 v138, v110, v111
	v_cvt_pk_bf16_f32 v139, v112, v113
	buffer_store_dwordx4 v[136:139], v140, s[8:11], 0 offen sc1
	s_waitcnt lgkmcnt(0)
	v_mul_f32_e32 v130, v134, v134
	ds_read_b32 v134, v196 offset:192
	v_pk_mul_f32 v[90:91], v[90:91], v[82:83]
	v_pk_mul_f32 v[92:93], v[92:93], v[84:85]
	v_pk_mul_f32 v[94:95], v[86:87], v[94:95]
	v_pk_mul_f32 v[96:97], v[88:89], v[96:97]
	v_pk_mul_f32 v[90:91], v[90:91], v[130:131] op_sel_hi:[1,0]
	v_pk_mul_f32 v[92:93], v[92:93], v[130:131] op_sel_hi:[1,0]
	v_pk_mul_f32 v[94:95], v[94:95], v[130:131] op_sel_hi:[1,0]
	v_pk_mul_f32 v[96:97], v[96:97], v[130:131] op_sel_hi:[1,0]
	v_or_b32_e32 v140, v179, v195
	v_lshlrev_b32_e32 v140, 1, v140
	s_nop 0
	v_cvt_pk_bf16_f32 v136, v90, v91
	v_cvt_pk_bf16_f32 v137, v92, v93
	v_cvt_pk_bf16_f32 v138, v94, v95
	v_cvt_pk_bf16_f32 v139, v96, v97
	buffer_store_dwordx4 v[136:139], v140, s[8:11], 0 offen sc1
	s_waitcnt lgkmcnt(0)
	v_mul_f32_e32 v130, v134, v134
	ds_read_b32 v134, v196 offset:512
	v_pk_mul_f32 v[74:75], v[74:75], v[66:67]
	v_pk_mul_f32 v[76:77], v[76:77], v[68:69]
	v_pk_mul_f32 v[78:79], v[70:71], v[78:79]
	v_pk_mul_f32 v[80:81], v[72:73], v[80:81]
	v_pk_mul_f32 v[74:75], v[74:75], v[130:131] op_sel_hi:[1,0]
	v_pk_mul_f32 v[76:77], v[76:77], v[130:131] op_sel_hi:[1,0]
	v_pk_mul_f32 v[78:79], v[78:79], v[130:131] op_sel_hi:[1,0]
	v_pk_mul_f32 v[80:81], v[80:81], v[130:131] op_sel_hi:[1,0]
	v_or_b32_e32 v140, v181, v195
	v_lshlrev_b32_e32 v140, 1, v140
	s_nop 0
	v_cvt_pk_bf16_f32 v136, v74, v75
	v_cvt_pk_bf16_f32 v137, v76, v77
	v_cvt_pk_bf16_f32 v138, v78, v79
	v_cvt_pk_bf16_f32 v139, v80, v81
	buffer_store_dwordx4 v[136:139], v140, s[8:11], 0 offen sc1
	s_waitcnt lgkmcnt(0)
	v_mul_f32_e32 v130, v134, v134
	ds_read_b32 v134, v196 offset:576
	v_pk_mul_f32 v[58:59], v[58:59], v[50:51]
	v_pk_mul_f32 v[60:61], v[60:61], v[52:53]
	v_pk_mul_f32 v[62:63], v[54:55], v[62:63]
	v_pk_mul_f32 v[64:65], v[56:57], v[64:65]
	v_pk_mul_f32 v[58:59], v[58:59], v[130:131] op_sel_hi:[1,0]
	v_pk_mul_f32 v[60:61], v[60:61], v[130:131] op_sel_hi:[1,0]
	v_pk_mul_f32 v[62:63], v[62:63], v[130:131] op_sel_hi:[1,0]
	v_pk_mul_f32 v[64:65], v[64:65], v[130:131] op_sel_hi:[1,0]
	v_or_b32_e32 v140, v183, v195
	v_lshlrev_b32_e32 v140, 1, v140
	s_nop 0
	v_cvt_pk_bf16_f32 v136, v58, v59
	v_cvt_pk_bf16_f32 v137, v60, v61
	v_cvt_pk_bf16_f32 v138, v62, v63
	v_cvt_pk_bf16_f32 v139, v64, v65
	buffer_store_dwordx4 v[136:139], v140, s[8:11], 0 offen sc1
	s_waitcnt lgkmcnt(0)
	v_mul_f32_e32 v130, v134, v134
	ds_read_b32 v134, v196 offset:640
	v_pk_mul_f32 v[42:43], v[42:43], v[34:35]
	v_pk_mul_f32 v[44:45], v[44:45], v[36:37]
	v_pk_mul_f32 v[46:47], v[38:39], v[46:47]
	v_pk_mul_f32 v[48:49], v[40:41], v[48:49]
	v_pk_mul_f32 v[42:43], v[42:43], v[130:131] op_sel_hi:[1,0]
	v_pk_mul_f32 v[44:45], v[44:45], v[130:131] op_sel_hi:[1,0]
	v_pk_mul_f32 v[46:47], v[46:47], v[130:131] op_sel_hi:[1,0]
	v_pk_mul_f32 v[48:49], v[48:49], v[130:131] op_sel_hi:[1,0]
	v_or_b32_e32 v140, v185, v195
	v_lshlrev_b32_e32 v140, 1, v140
	s_nop 0
	v_cvt_pk_bf16_f32 v136, v42, v43
	v_cvt_pk_bf16_f32 v137, v44, v45
	v_cvt_pk_bf16_f32 v138, v46, v47
	v_cvt_pk_bf16_f32 v139, v48, v49
	buffer_store_dwordx4 v[136:139], v140, s[8:11], 0 offen sc1
	s_waitcnt lgkmcnt(0)
	v_mul_f32_e32 v130, v134, v134
	ds_read_b32 v134, v196 offset:704
	v_pk_mul_f32 v[26:27], v[26:27], v[18:19]
	v_pk_mul_f32 v[28:29], v[28:29], v[20:21]
	v_pk_mul_f32 v[30:31], v[22:23], v[30:31]
	v_pk_mul_f32 v[32:33], v[24:25], v[32:33]
	v_pk_mul_f32 v[26:27], v[26:27], v[130:131] op_sel_hi:[1,0]
	v_pk_mul_f32 v[28:29], v[28:29], v[130:131] op_sel_hi:[1,0]
	v_pk_mul_f32 v[30:31], v[30:31], v[130:131] op_sel_hi:[1,0]
	v_pk_mul_f32 v[32:33], v[32:33], v[130:131] op_sel_hi:[1,0]
	v_or_b32_e32 v140, v187, v195
	v_lshlrev_b32_e32 v140, 1, v140
	s_nop 0
	v_cvt_pk_bf16_f32 v136, v26, v27
	v_cvt_pk_bf16_f32 v137, v28, v29
	v_cvt_pk_bf16_f32 v138, v30, v31
	v_cvt_pk_bf16_f32 v139, v32, v33
	buffer_store_dwordx4 v[136:139], v140, s[8:11], 0 offen sc1
	s_waitcnt lgkmcnt(0)
	v_mul_f32_e32 v130, v134, v134
	v_pk_mul_f32 v[10:11], v[10:11], v[2:3]
	v_pk_mul_f32 v[12:13], v[12:13], v[4:5]
	v_pk_mul_f32 v[14:15], v[6:7], v[14:15]
	v_pk_mul_f32 v[16:17], v[8:9], v[16:17]
	v_pk_mul_f32 v[10:11], v[10:11], v[130:131] op_sel_hi:[1,0]
	v_pk_mul_f32 v[12:13], v[12:13], v[130:131] op_sel_hi:[1,0]
	v_pk_mul_f32 v[14:15], v[14:15], v[130:131] op_sel_hi:[1,0]
	v_pk_mul_f32 v[16:17], v[16:17], v[130:131] op_sel_hi:[1,0]
	v_or_b32_e32 v140, v191, v195
	v_lshlrev_b32_e32 v140, 1, v140
	s_nop 0
	v_cvt_pk_bf16_f32 v136, v10, v11
	v_cvt_pk_bf16_f32 v137, v12, v13
	v_cvt_pk_bf16_f32 v138, v14, v15
	v_cvt_pk_bf16_f32 v139, v16, v17
	buffer_store_dwordx4 v[136:139], v140, s[8:11], 0 offen sc1
	s_branch .Lp3_cugb_done
.Lp3_gb_path:
	s_waitcnt lgkmcnt(0)
	v_mul_f32_e32 v132, 0xbfb8aa3b, v134
	v_mov_b32_e32 v130, v134
	ds_read_b32 v134, v196 offset:64
	v_pk_mul_f32 v[114:115], v[114:115], v[132:133] op_sel_hi:[1,0]
	v_pk_mul_f32 v[116:117], v[116:117], v[132:133] op_sel_hi:[1,0]
	v_pk_mul_f32 v[118:119], v[118:119], v[132:133] op_sel_hi:[1,0]
	v_pk_mul_f32 v[120:121], v[120:121], v[132:133] op_sel_hi:[1,0]
	v_exp_f32_e32 v114, v114
	v_exp_f32_e32 v115, v115
	v_exp_f32_e32 v116, v116
	v_exp_f32_e32 v117, v117
	v_exp_f32_e32 v118, v118
	v_exp_f32_e32 v119, v119
	v_exp_f32_e32 v120, v120
	v_exp_f32_e32 v121, v121
	v_add_f32_e32 v114, 1.0, v114
	v_add_f32_e32 v115, 1.0, v115
	v_add_f32_e32 v116, 1.0, v116
	v_add_f32_e32 v117, 1.0, v117
	v_add_f32_e32 v118, 1.0, v118
	v_add_f32_e32 v119, 1.0, v119
	v_add_f32_e32 v120, 1.0, v120
	v_add_f32_e32 v121, 1.0, v121
	v_rcp_f32_e32 v114, v114
	v_rcp_f32_e32 v115, v115
	v_rcp_f32_e32 v116, v116
	v_rcp_f32_e32 v117, v117
	v_rcp_f32_e32 v118, v118
	v_rcp_f32_e32 v119, v119
	v_rcp_f32_e32 v120, v120
	v_rcp_f32_e32 v121, v121
	v_pk_mul_f32 v[122:123], v[122:123], v[130:131] op_sel_hi:[1,0]
	v_pk_mul_f32 v[124:125], v[124:125], v[130:131] op_sel_hi:[1,0]
	v_pk_mul_f32 v[126:127], v[126:127], v[130:131] op_sel_hi:[1,0]
	v_pk_mul_f32 v[128:129], v[128:129], v[130:131] op_sel_hi:[1,0]
	v_pk_mul_f32 v[122:123], v[122:123], v[114:115]
	v_pk_mul_f32 v[124:125], v[124:125], v[116:117]
	v_pk_mul_f32 v[126:127], v[118:119], v[126:127]
	v_pk_mul_f32 v[128:129], v[120:121], v[128:129]
	v_or_b32_e32 v140, v158, v195
	v_lshlrev_b32_e32 v140, 1, v140
	s_nop 0
	v_cvt_pk_bf16_f32 v136, v122, v123
	v_cvt_pk_bf16_f32 v137, v124, v125
	v_cvt_pk_bf16_f32 v138, v126, v127
	v_cvt_pk_bf16_f32 v139, v128, v129
	buffer_store_dwordx4 v[136:139], v140, s[8:11], 0 offen sc1
	s_waitcnt lgkmcnt(0)
	v_mul_f32_e32 v132, 0xbfb8aa3b, v134
	v_mov_b32_e32 v130, v134
	ds_read_b32 v134, v196 offset:128
	v_pk_mul_f32 v[98:99], v[98:99], v[132:133] op_sel_hi:[1,0]
	v_pk_mul_f32 v[100:101], v[100:101], v[132:133] op_sel_hi:[1,0]
	v_pk_mul_f32 v[102:103], v[102:103], v[132:133] op_sel_hi:[1,0]
	v_pk_mul_f32 v[104:105], v[104:105], v[132:133] op_sel_hi:[1,0]
	v_exp_f32_e32 v98, v98
	v_exp_f32_e32 v99, v99
	v_exp_f32_e32 v100, v100
	v_exp_f32_e32 v101, v101
	v_exp_f32_e32 v102, v102
	v_exp_f32_e32 v103, v103
	v_exp_f32_e32 v104, v104
	v_exp_f32_e32 v105, v105
	v_add_f32_e32 v98, 1.0, v98
	v_add_f32_e32 v99, 1.0, v99
	v_add_f32_e32 v100, 1.0, v100
	v_add_f32_e32 v101, 1.0, v101
	v_add_f32_e32 v102, 1.0, v102
	v_add_f32_e32 v103, 1.0, v103
	v_add_f32_e32 v104, 1.0, v104
	v_add_f32_e32 v105, 1.0, v105
	v_rcp_f32_e32 v98, v98
	v_rcp_f32_e32 v99, v99
	v_rcp_f32_e32 v100, v100
	v_rcp_f32_e32 v101, v101
	v_rcp_f32_e32 v102, v102
	v_rcp_f32_e32 v103, v103
	v_rcp_f32_e32 v104, v104
	v_rcp_f32_e32 v105, v105
	v_pk_mul_f32 v[106:107], v[106:107], v[130:131] op_sel_hi:[1,0]
	v_pk_mul_f32 v[108:109], v[108:109], v[130:131] op_sel_hi:[1,0]
	v_pk_mul_f32 v[110:111], v[110:111], v[130:131] op_sel_hi:[1,0]
	v_pk_mul_f32 v[112:113], v[112:113], v[130:131] op_sel_hi:[1,0]
	v_pk_mul_f32 v[106:107], v[106:107], v[98:99]
	v_pk_mul_f32 v[108:109], v[108:109], v[100:101]
	v_pk_mul_f32 v[110:111], v[102:103], v[110:111]
	v_pk_mul_f32 v[112:113], v[104:105], v[112:113]
	v_or_b32_e32 v140, v178, v195
	v_lshlrev_b32_e32 v140, 1, v140
	s_nop 0
	v_cvt_pk_bf16_f32 v136, v106, v107
	v_cvt_pk_bf16_f32 v137, v108, v109
	v_cvt_pk_bf16_f32 v138, v110, v111
	v_cvt_pk_bf16_f32 v139, v112, v113
	buffer_store_dwordx4 v[136:139], v140, s[8:11], 0 offen sc1
	s_waitcnt lgkmcnt(0)
	v_mul_f32_e32 v132, 0xbfb8aa3b, v134
	v_mov_b32_e32 v130, v134
	ds_read_b32 v134, v196 offset:192
	v_pk_mul_f32 v[82:83], v[82:83], v[132:133] op_sel_hi:[1,0]
	v_pk_mul_f32 v[84:85], v[84:85], v[132:133] op_sel_hi:[1,0]
	v_pk_mul_f32 v[86:87], v[86:87], v[132:133] op_sel_hi:[1,0]
	v_pk_mul_f32 v[88:89], v[88:89], v[132:133] op_sel_hi:[1,0]
	v_exp_f32_e32 v82, v82
	v_exp_f32_e32 v83, v83
	v_exp_f32_e32 v84, v84
	v_exp_f32_e32 v85, v85
	v_exp_f32_e32 v86, v86
	v_exp_f32_e32 v87, v87
	v_exp_f32_e32 v88, v88
	v_exp_f32_e32 v89, v89
	v_add_f32_e32 v82, 1.0, v82
	v_add_f32_e32 v83, 1.0, v83
	v_add_f32_e32 v84, 1.0, v84
	v_add_f32_e32 v85, 1.0, v85
	v_add_f32_e32 v86, 1.0, v86
	v_add_f32_e32 v87, 1.0, v87
	v_add_f32_e32 v88, 1.0, v88
	v_add_f32_e32 v89, 1.0, v89
	v_rcp_f32_e32 v82, v82
	v_rcp_f32_e32 v83, v83
	v_rcp_f32_e32 v84, v84
	v_rcp_f32_e32 v85, v85
	v_rcp_f32_e32 v86, v86
	v_rcp_f32_e32 v87, v87
	v_rcp_f32_e32 v88, v88
	v_rcp_f32_e32 v89, v89
	v_pk_mul_f32 v[90:91], v[90:91], v[130:131] op_sel_hi:[1,0]
	v_pk_mul_f32 v[92:93], v[92:93], v[130:131] op_sel_hi:[1,0]
	v_pk_mul_f32 v[94:95], v[94:95], v[130:131] op_sel_hi:[1,0]
	v_pk_mul_f32 v[96:97], v[96:97], v[130:131] op_sel_hi:[1,0]
	v_pk_mul_f32 v[90:91], v[90:91], v[82:83]
	v_pk_mul_f32 v[92:93], v[92:93], v[84:85]
	v_pk_mul_f32 v[94:95], v[86:87], v[94:95]
	v_pk_mul_f32 v[96:97], v[88:89], v[96:97]
	v_or_b32_e32 v140, v180, v195
	v_lshlrev_b32_e32 v140, 1, v140
	s_nop 0
	v_cvt_pk_bf16_f32 v136, v90, v91
	v_cvt_pk_bf16_f32 v137, v92, v93
	v_cvt_pk_bf16_f32 v138, v94, v95
	v_cvt_pk_bf16_f32 v139, v96, v97
	buffer_store_dwordx4 v[136:139], v140, s[8:11], 0 offen sc1
	s_waitcnt lgkmcnt(0)
	v_mul_f32_e32 v132, 0xbfb8aa3b, v134
	v_mov_b32_e32 v130, v134
	ds_read_b32 v134, v196 offset:512
	v_pk_mul_f32 v[66:67], v[66:67], v[132:133] op_sel_hi:[1,0]
	v_pk_mul_f32 v[68:69], v[68:69], v[132:133] op_sel_hi:[1,0]
	v_pk_mul_f32 v[70:71], v[70:71], v[132:133] op_sel_hi:[1,0]
	v_pk_mul_f32 v[72:73], v[72:73], v[132:133] op_sel_hi:[1,0]
	v_exp_f32_e32 v66, v66
	v_exp_f32_e32 v67, v67
	v_exp_f32_e32 v68, v68
	v_exp_f32_e32 v69, v69
	v_exp_f32_e32 v70, v70
	v_exp_f32_e32 v71, v71
	v_exp_f32_e32 v72, v72
	v_exp_f32_e32 v73, v73
	v_add_f32_e32 v66, 1.0, v66
	v_add_f32_e32 v67, 1.0, v67
	v_add_f32_e32 v68, 1.0, v68
	v_add_f32_e32 v69, 1.0, v69
	v_add_f32_e32 v70, 1.0, v70
	v_add_f32_e32 v71, 1.0, v71
	v_add_f32_e32 v72, 1.0, v72
	v_add_f32_e32 v73, 1.0, v73
	v_rcp_f32_e32 v66, v66
	v_rcp_f32_e32 v67, v67
	v_rcp_f32_e32 v68, v68
	v_rcp_f32_e32 v69, v69
	v_rcp_f32_e32 v70, v70
	v_rcp_f32_e32 v71, v71
	v_rcp_f32_e32 v72, v72
	v_rcp_f32_e32 v73, v73
	v_pk_mul_f32 v[74:75], v[74:75], v[130:131] op_sel_hi:[1,0]
	v_pk_mul_f32 v[76:77], v[76:77], v[130:131] op_sel_hi:[1,0]
	v_pk_mul_f32 v[78:79], v[78:79], v[130:131] op_sel_hi:[1,0]
	v_pk_mul_f32 v[80:81], v[80:81], v[130:131] op_sel_hi:[1,0]
	v_pk_mul_f32 v[74:75], v[74:75], v[66:67]
	v_pk_mul_f32 v[76:77], v[76:77], v[68:69]
	v_pk_mul_f32 v[78:79], v[70:71], v[78:79]
	v_pk_mul_f32 v[80:81], v[72:73], v[80:81]
	v_or_b32_e32 v140, v182, v195
	v_lshlrev_b32_e32 v140, 1, v140
	s_nop 0
	v_cvt_pk_bf16_f32 v136, v74, v75
	v_cvt_pk_bf16_f32 v137, v76, v77
	v_cvt_pk_bf16_f32 v138, v78, v79
	v_cvt_pk_bf16_f32 v139, v80, v81
	buffer_store_dwordx4 v[136:139], v140, s[8:11], 0 offen sc1
	s_waitcnt lgkmcnt(0)
	v_mul_f32_e32 v132, 0xbfb8aa3b, v134
	v_mov_b32_e32 v130, v134
	ds_read_b32 v134, v196 offset:576
	v_pk_mul_f32 v[50:51], v[50:51], v[132:133] op_sel_hi:[1,0]
	v_pk_mul_f32 v[52:53], v[52:53], v[132:133] op_sel_hi:[1,0]
	v_pk_mul_f32 v[54:55], v[54:55], v[132:133] op_sel_hi:[1,0]
	v_pk_mul_f32 v[56:57], v[56:57], v[132:133] op_sel_hi:[1,0]
	v_exp_f32_e32 v50, v50
	v_exp_f32_e32 v51, v51
	v_exp_f32_e32 v52, v52
	v_exp_f32_e32 v53, v53
	v_exp_f32_e32 v54, v54
	v_exp_f32_e32 v55, v55
	v_exp_f32_e32 v56, v56
	v_exp_f32_e32 v57, v57
	v_add_f32_e32 v50, 1.0, v50
	v_add_f32_e32 v51, 1.0, v51
	v_add_f32_e32 v52, 1.0, v52
	v_add_f32_e32 v53, 1.0, v53
	v_add_f32_e32 v54, 1.0, v54
	v_add_f32_e32 v55, 1.0, v55
	v_add_f32_e32 v56, 1.0, v56
	v_add_f32_e32 v57, 1.0, v57
	v_rcp_f32_e32 v50, v50
	v_rcp_f32_e32 v51, v51
	v_rcp_f32_e32 v52, v52
	v_rcp_f32_e32 v53, v53
	v_rcp_f32_e32 v54, v54
	v_rcp_f32_e32 v55, v55
	v_rcp_f32_e32 v56, v56
	v_rcp_f32_e32 v57, v57
	v_pk_mul_f32 v[58:59], v[58:59], v[130:131] op_sel_hi:[1,0]
	v_pk_mul_f32 v[60:61], v[60:61], v[130:131] op_sel_hi:[1,0]
	v_pk_mul_f32 v[62:63], v[62:63], v[130:131] op_sel_hi:[1,0]
	v_pk_mul_f32 v[64:65], v[64:65], v[130:131] op_sel_hi:[1,0]
	v_pk_mul_f32 v[58:59], v[58:59], v[50:51]
	v_pk_mul_f32 v[60:61], v[60:61], v[52:53]
	v_pk_mul_f32 v[62:63], v[54:55], v[62:63]
	v_pk_mul_f32 v[64:65], v[56:57], v[64:65]
	v_or_b32_e32 v140, v184, v195
	v_lshlrev_b32_e32 v140, 1, v140
	s_nop 0
	v_cvt_pk_bf16_f32 v136, v58, v59
	v_cvt_pk_bf16_f32 v137, v60, v61
	v_cvt_pk_bf16_f32 v138, v62, v63
	v_cvt_pk_bf16_f32 v139, v64, v65
	buffer_store_dwordx4 v[136:139], v140, s[8:11], 0 offen sc1
	s_waitcnt lgkmcnt(0)
	v_mul_f32_e32 v132, 0xbfb8aa3b, v134
	v_mov_b32_e32 v130, v134
	ds_read_b32 v134, v196 offset:640
	v_pk_mul_f32 v[34:35], v[34:35], v[132:133] op_sel_hi:[1,0]
	v_pk_mul_f32 v[36:37], v[36:37], v[132:133] op_sel_hi:[1,0]
	v_pk_mul_f32 v[38:39], v[38:39], v[132:133] op_sel_hi:[1,0]
	v_pk_mul_f32 v[40:41], v[40:41], v[132:133] op_sel_hi:[1,0]
	v_exp_f32_e32 v34, v34
	v_exp_f32_e32 v35, v35
	v_exp_f32_e32 v36, v36
	v_exp_f32_e32 v37, v37
	v_exp_f32_e32 v38, v38
	v_exp_f32_e32 v39, v39
	v_exp_f32_e32 v40, v40
	v_exp_f32_e32 v41, v41
	v_add_f32_e32 v34, 1.0, v34
	v_add_f32_e32 v35, 1.0, v35
	v_add_f32_e32 v36, 1.0, v36
	v_add_f32_e32 v37, 1.0, v37
	v_add_f32_e32 v38, 1.0, v38
	v_add_f32_e32 v39, 1.0, v39
	v_add_f32_e32 v40, 1.0, v40
	v_add_f32_e32 v41, 1.0, v41
	v_rcp_f32_e32 v34, v34
	v_rcp_f32_e32 v35, v35
	v_rcp_f32_e32 v36, v36
	v_rcp_f32_e32 v37, v37
	v_rcp_f32_e32 v38, v38
	v_rcp_f32_e32 v39, v39
	v_rcp_f32_e32 v40, v40
	v_rcp_f32_e32 v41, v41
	v_pk_mul_f32 v[42:43], v[42:43], v[130:131] op_sel_hi:[1,0]
	v_pk_mul_f32 v[44:45], v[44:45], v[130:131] op_sel_hi:[1,0]
	v_pk_mul_f32 v[46:47], v[46:47], v[130:131] op_sel_hi:[1,0]
	v_pk_mul_f32 v[48:49], v[48:49], v[130:131] op_sel_hi:[1,0]
	v_pk_mul_f32 v[42:43], v[42:43], v[34:35]
	v_pk_mul_f32 v[44:45], v[44:45], v[36:37]
	v_pk_mul_f32 v[46:47], v[38:39], v[46:47]
	v_pk_mul_f32 v[48:49], v[40:41], v[48:49]
	v_or_b32_e32 v140, v186, v195
	v_lshlrev_b32_e32 v140, 1, v140
	s_nop 0
	v_cvt_pk_bf16_f32 v136, v42, v43
	v_cvt_pk_bf16_f32 v137, v44, v45
	v_cvt_pk_bf16_f32 v138, v46, v47
	v_cvt_pk_bf16_f32 v139, v48, v49
	buffer_store_dwordx4 v[136:139], v140, s[8:11], 0 offen sc1
	s_waitcnt lgkmcnt(0)
	v_mul_f32_e32 v132, 0xbfb8aa3b, v134
	v_mov_b32_e32 v130, v134
	ds_read_b32 v134, v196 offset:704
	v_pk_mul_f32 v[18:19], v[18:19], v[132:133] op_sel_hi:[1,0]
	v_pk_mul_f32 v[20:21], v[20:21], v[132:133] op_sel_hi:[1,0]
	v_pk_mul_f32 v[22:23], v[22:23], v[132:133] op_sel_hi:[1,0]
	v_pk_mul_f32 v[24:25], v[24:25], v[132:133] op_sel_hi:[1,0]
	v_exp_f32_e32 v18, v18
	v_exp_f32_e32 v19, v19
	v_exp_f32_e32 v20, v20
	v_exp_f32_e32 v21, v21
	v_exp_f32_e32 v22, v22
	v_exp_f32_e32 v23, v23
	v_exp_f32_e32 v24, v24
	v_exp_f32_e32 v25, v25
	v_add_f32_e32 v18, 1.0, v18
	v_add_f32_e32 v19, 1.0, v19
	v_add_f32_e32 v20, 1.0, v20
	v_add_f32_e32 v21, 1.0, v21
	v_add_f32_e32 v22, 1.0, v22
	v_add_f32_e32 v23, 1.0, v23
	v_add_f32_e32 v24, 1.0, v24
	v_add_f32_e32 v25, 1.0, v25
	v_rcp_f32_e32 v18, v18
	v_rcp_f32_e32 v19, v19
	v_rcp_f32_e32 v20, v20
	v_rcp_f32_e32 v21, v21
	v_rcp_f32_e32 v22, v22
	v_rcp_f32_e32 v23, v23
	v_rcp_f32_e32 v24, v24
	v_rcp_f32_e32 v25, v25
	v_pk_mul_f32 v[26:27], v[26:27], v[130:131] op_sel_hi:[1,0]
	v_pk_mul_f32 v[28:29], v[28:29], v[130:131] op_sel_hi:[1,0]
	v_pk_mul_f32 v[30:31], v[30:31], v[130:131] op_sel_hi:[1,0]
	v_pk_mul_f32 v[32:33], v[32:33], v[130:131] op_sel_hi:[1,0]
	v_pk_mul_f32 v[26:27], v[26:27], v[18:19]
	v_pk_mul_f32 v[28:29], v[28:29], v[20:21]
	v_pk_mul_f32 v[30:31], v[22:23], v[30:31]
	v_pk_mul_f32 v[32:33], v[24:25], v[32:33]
	v_or_b32_e32 v140, v189, v195
	v_lshlrev_b32_e32 v140, 1, v140
	s_nop 0
	v_cvt_pk_bf16_f32 v136, v26, v27
	v_cvt_pk_bf16_f32 v137, v28, v29
	v_cvt_pk_bf16_f32 v138, v30, v31
	v_cvt_pk_bf16_f32 v139, v32, v33
	buffer_store_dwordx4 v[136:139], v140, s[8:11], 0 offen sc1
	s_waitcnt lgkmcnt(0)
	v_mul_f32_e32 v132, 0xbfb8aa3b, v134
	v_mov_b32_e32 v130, v134
	v_pk_mul_f32 v[2:3], v[2:3], v[132:133] op_sel_hi:[1,0]
	v_pk_mul_f32 v[4:5], v[4:5], v[132:133] op_sel_hi:[1,0]
	v_pk_mul_f32 v[6:7], v[6:7], v[132:133] op_sel_hi:[1,0]
	v_pk_mul_f32 v[8:9], v[8:9], v[132:133] op_sel_hi:[1,0]
	v_exp_f32_e32 v2, v2
	v_exp_f32_e32 v3, v3
	v_exp_f32_e32 v4, v4
	v_exp_f32_e32 v5, v5
	v_exp_f32_e32 v6, v6
	v_exp_f32_e32 v7, v7
	v_exp_f32_e32 v8, v8
	v_exp_f32_e32 v9, v9
	v_add_f32_e32 v2, 1.0, v2
	v_add_f32_e32 v3, 1.0, v3
	v_add_f32_e32 v4, 1.0, v4
	v_add_f32_e32 v5, 1.0, v5
	v_add_f32_e32 v6, 1.0, v6
	v_add_f32_e32 v7, 1.0, v7
	v_add_f32_e32 v8, 1.0, v8
	v_add_f32_e32 v9, 1.0, v9
	v_rcp_f32_e32 v2, v2
	v_rcp_f32_e32 v3, v3
	v_rcp_f32_e32 v4, v4
	v_rcp_f32_e32 v5, v5
	v_rcp_f32_e32 v6, v6
	v_rcp_f32_e32 v7, v7
	v_rcp_f32_e32 v8, v8
	v_rcp_f32_e32 v9, v9
	v_pk_mul_f32 v[10:11], v[10:11], v[130:131] op_sel_hi:[1,0]
	v_pk_mul_f32 v[12:13], v[12:13], v[130:131] op_sel_hi:[1,0]
	v_pk_mul_f32 v[14:15], v[14:15], v[130:131] op_sel_hi:[1,0]
	v_pk_mul_f32 v[16:17], v[16:17], v[130:131] op_sel_hi:[1,0]
	v_pk_mul_f32 v[10:11], v[10:11], v[2:3]
	v_pk_mul_f32 v[12:13], v[12:13], v[4:5]
	v_pk_mul_f32 v[14:15], v[6:7], v[14:15]
	v_pk_mul_f32 v[16:17], v[8:9], v[16:17]
	v_or_b32_e32 v140, v192, v195
	v_lshlrev_b32_e32 v140, 1, v140
	s_nop 0
	v_cvt_pk_bf16_f32 v136, v10, v11
	v_cvt_pk_bf16_f32 v137, v12, v13
	v_cvt_pk_bf16_f32 v138, v14, v15
	v_cvt_pk_bf16_f32 v139, v16, v17
	buffer_store_dwordx4 v[136:139], v140, s[8:11], 0 offen sc1
.Lp3_cugb_done:
	s_branch .LBB0_604
.LBB0_529:
	s_and_b64 vcc, exec, s[4:5]
	s_cbranch_vccz .LBB0_604
	s_cmp_gt_i32 s46, 3
	s_mov_b64 s[4:5], -1
	s_cbranch_scc0 .LBB0_537
	s_cmp_lt_i32 s46, 5
	s_cbranch_scc1 .LBB0_536
	s_cmp_lg_u32 s46, 5
	s_cbranch_scc0 .LBB0_534
	s_lshl_b32 s4, s46, 8
	s_add_i32 s4, s14, s4
	s_ashr_i32 s4, s4, 5
	s_ashr_i32 s5, s4, 31
	s_lshl_b64 s[4:5], s[4:5], 6
	v_lshl_add_u64 v[130:131], v[164:165], 0, s[4:5]
	s_mov_b64 s[4:5], 0
